# P5->P6 seam: group-local sync plus a global 'P5 K-loop done' counter instead of the grid barrier; U stored write-through in P4 so nothing dirty lies under ACT
# speedup vs baseline: 1.0089x; 1.0059x over previous
; __device__ __forceinline__ u32x4 pack8(const float (&v)[8]) { u32x4 w; w.x = cvtpk(v[0], v[1]); w.y = cvtpk(v[2], v[3]); w.z = cvtpk(v[4], v[5]); w.w = cvtpk(v[6], v[7]); return w; }
;     __device__ __forceinline__ void operator()(pg8::f32x4 (&acc)[2][2][4][2], const pg8::Unit& u, int wr, int wc, int fr, int fq) const {
;     ...
;                     const int row = u.pm * 256 + ai * 128 + wr * 64 + m * 16 + fr, c0 = u.pn * 256 + bj * 128 + wc * 32 + 8 * fq;
;                     if (u.seg == 0) { float rr[8]; unpack8(__builtin_nontemporal_load((const u32x4*)(GATES + (size_t)row * 2048 + 1024 + c0)), rr);
; #pragma unroll
;                         for (int i = 0; i < 8; ++i) acc[ai][bj][m][i >> 2][i & 3] *= rr[i];
;                     } else { float ga[8], o[8]; unpack8(__builtin_nontemporal_load((const u32x4*)(GATES + (size_t)row * 2048 + c0)), ga);
; #pragma unroll
;                         for (int i = 0; i < 8; ++i) o[i] = ga[i] * acc[ai][bj][m][i >> 2][i & 3];
;                         *(u32x4*)(U + (size_t)row * DM + c0) = pack8(o); }
.Lp4e_seg1:
	v_add_u32_e32 v161, s19, v150
	v_lshl_add_u32 v161, v161, 12, v240
	global_load_dwordx4 v[162:165], v161, s[10:11] offset:0 nt
	global_load_dwordx4 v[166:169], v161, s[10:11] offset:256 nt
	v_add_u32_e32 v161, s19, v152
	v_lshl_add_u32 v161, v161, 12, v240
	global_load_dwordx4 v[170:173], v161, s[10:11] offset:0 nt
	global_load_dwordx4 v[174:177], v161, s[10:11] offset:256 nt
	v_add_u32_e32 v161, s19, v153
	v_lshl_add_u32 v161, v161, 12, v240
	global_load_dwordx4 v[178:181], v161, s[10:11] offset:0 nt
	global_load_dwordx4 v[182:185], v161, s[10:11] offset:256 nt
	v_add_u32_e32 v161, s19, v154
	v_lshl_add_u32 v161, v161, 12, v240
	global_load_dwordx4 v[186:189], v161, s[10:11] offset:0 nt
	global_load_dwordx4 v[190:193], v161, s[10:11] offset:256 nt
	v_add_u32_e32 v161, s19, v155
	v_lshl_add_u32 v161, v161, 12, v240
	global_load_dwordx4 v[194:197], v161, s[10:11] offset:0 nt
	global_load_dwordx4 v[198:201], v161, s[10:11] offset:256 nt
	v_add_u32_e32 v161, s19, v156
	v_lshl_add_u32 v161, v161, 12, v240
	global_load_dwordx4 v[202:205], v161, s[10:11] offset:0 nt
	global_load_dwordx4 v[210:213], v161, s[10:11] offset:256 nt
	v_add_u32_e32 v161, s19, v157
	v_lshl_add_u32 v161, v161, 12, v240
	global_load_dwordx4 v[214:217], v161, s[10:11] offset:0 nt
	global_load_dwordx4 v[218:221], v161, s[10:11] offset:256 nt
	v_add_u32_e32 v161, s19, v158
	v_lshl_add_u32 v161, v161, 12, v240
	global_load_dwordx4 v[222:225], v161, s[10:11] offset:0 nt
	global_load_dwordx4 v[144:147], v161, s[10:11] offset:256 nt
	s_waitcnt vmcnt(15)
	v_lshlrev_b32_e32 v148, 16, v162
	v_and_b32_e32 v149, 0xffff0000, v162
	v_lshlrev_b32_e32 v238, 16, v163
	v_and_b32_e32 v239, 0xffff0000, v163
	v_lshlrev_b32_e32 v162, 16, v164
	v_and_b32_e32 v163, 0xffff0000, v164
	v_lshlrev_b32_e32 v164, 16, v165
	v_and_b32_e32 v165, 0xffff0000, v165
	v_pk_mul_f32 v[148:149], v[124:125], v[148:149]
	v_pk_mul_f32 v[238:239], v[126:127], v[238:239]
	v_pk_mul_f32 v[162:163], v[120:121], v[162:163]
	v_pk_mul_f32 v[164:165], v[122:123], v[164:165]
	v_add_u32_e32 v241, s19, v150
	v_lshl_add_u32 v241, v241, 11, v240
	v_cvt_pk_bf16_f32 v165, v164, v165
	v_cvt_pk_bf16_f32 v164, v162, v163
	v_cvt_pk_bf16_f32 v162, v148, v149
	v_cvt_pk_bf16_f32 v163, v238, v239
	global_store_dwordx4 v241, v[162:165], s[12:13] offset:0 sc1
	s_waitcnt vmcnt(15)
	v_lshlrev_b32_e32 v148, 16, v166
	v_and_b32_e32 v149, 0xffff0000, v166
	v_lshlrev_b32_e32 v238, 16, v167
	v_and_b32_e32 v239, 0xffff0000, v167
	v_lshlrev_b32_e32 v166, 16, v168
	v_and_b32_e32 v167, 0xffff0000, v168
	v_lshlrev_b32_e32 v168, 16, v169
	v_and_b32_e32 v169, 0xffff0000, v169
	v_pk_mul_f32 v[148:149], v[92:93], v[148:149]
	v_pk_mul_f32 v[238:239], v[94:95], v[238:239]
	v_pk_mul_f32 v[166:167], v[88:89], v[166:167]
	v_pk_mul_f32 v[168:169], v[90:91], v[168:169]
	v_cvt_pk_bf16_f32 v169, v168, v169
	v_cvt_pk_bf16_f32 v168, v166, v167
	v_cvt_pk_bf16_f32 v166, v148, v149
	v_cvt_pk_bf16_f32 v167, v238, v239
	global_store_dwordx4 v241, v[166:169], s[12:13] offset:256 sc1
	s_waitcnt vmcnt(15)
	v_lshlrev_b32_e32 v148, 16, v170
	v_and_b32_e32 v149, 0xffff0000, v170
	v_lshlrev_b32_e32 v238, 16, v171
	v_and_b32_e32 v239, 0xffff0000, v171
	v_lshlrev_b32_e32 v170, 16, v172
	v_and_b32_e32 v171, 0xffff0000, v172
	v_lshlrev_b32_e32 v172, 16, v173
	v_and_b32_e32 v173, 0xffff0000, v173
	v_pk_mul_f32 v[148:149], v[116:117], v[148:149]
	v_pk_mul_f32 v[238:239], v[118:119], v[238:239]
	v_pk_mul_f32 v[170:171], v[112:113], v[170:171]
	v_pk_mul_f32 v[172:173], v[114:115], v[172:173]
	v_add_u32_e32 v241, s19, v152
	v_lshl_add_u32 v241, v241, 11, v240
	v_cvt_pk_bf16_f32 v173, v172, v173
	v_cvt_pk_bf16_f32 v172, v170, v171
	v_cvt_pk_bf16_f32 v170, v148, v149
	v_cvt_pk_bf16_f32 v171, v238, v239
	global_store_dwordx4 v241, v[170:173], s[12:13] offset:0 sc1
	s_waitcnt vmcnt(15)
	v_lshlrev_b32_e32 v148, 16, v174
	v_and_b32_e32 v149, 0xffff0000, v174
	v_lshlrev_b32_e32 v238, 16, v175
	v_and_b32_e32 v239, 0xffff0000, v175
	v_lshlrev_b32_e32 v174, 16, v176
	v_and_b32_e32 v175, 0xffff0000, v176
	v_lshlrev_b32_e32 v176, 16, v177
	v_and_b32_e32 v177, 0xffff0000, v177
	v_pk_mul_f32 v[148:149], v[84:85], v[148:149]
	v_pk_mul_f32 v[238:239], v[86:87], v[238:239]
	v_pk_mul_f32 v[174:175], v[80:81], v[174:175]
	v_pk_mul_f32 v[176:177], v[82:83], v[176:177]
	v_cvt_pk_bf16_f32 v177, v176, v177
	v_cvt_pk_bf16_f32 v176, v174, v175
	v_cvt_pk_bf16_f32 v174, v148, v149
	v_cvt_pk_bf16_f32 v175, v238, v239
	global_store_dwordx4 v241, v[174:177], s[12:13] offset:256 sc1
	s_waitcnt vmcnt(15)
	v_lshlrev_b32_e32 v148, 16, v178
	v_and_b32_e32 v149, 0xffff0000, v178
	v_lshlrev_b32_e32 v238, 16, v179
	v_and_b32_e32 v239, 0xffff0000, v179
	v_lshlrev_b32_e32 v178, 16, v180
	v_and_b32_e32 v179, 0xffff0000, v180
	v_lshlrev_b32_e32 v180, 16, v181
	v_and_b32_e32 v181, 0xffff0000, v181
	v_pk_mul_f32 v[148:149], v[108:109], v[148:149]
	v_pk_mul_f32 v[238:239], v[110:111], v[238:239]
	v_pk_mul_f32 v[178:179], v[104:105], v[178:179]
	v_pk_mul_f32 v[180:181], v[106:107], v[180:181]
	v_add_u32_e32 v241, s19, v153
	v_lshl_add_u32 v241, v241, 11, v240
	v_cvt_pk_bf16_f32 v181, v180, v181
	v_cvt_pk_bf16_f32 v180, v178, v179
	v_cvt_pk_bf16_f32 v178, v148, v149
	v_cvt_pk_bf16_f32 v179, v238, v239
	global_store_dwordx4 v241, v[178:181], s[12:13] offset:0 sc1
	s_waitcnt vmcnt(15)
; __device__ __forceinline__ u32x4 pack8(const float (&v)[8]) { u32x4 w; w.x = cvtpk(v[0], v[1]); w.y = cvtpk(v[2], v[3]); w.z = cvtpk(v[4], v[5]); w.w = cvtpk(v[6], v[7]); return w; }
;     __device__ __forceinline__ void operator()(pg8::f32x4 (&acc)[2][2][4][2], const pg8::Unit& u, int wr, int wc, int fr, int fq) const {
;     ...
;                     const int row = u.pm * 256 + ai * 128 + wr * 64 + m * 16 + fr, c0 = u.pn * 256 + bj * 128 + wc * 32 + 8 * fq;
;                     if (u.seg == 0) { float rr[8]; unpack8(__builtin_nontemporal_load((const u32x4*)(GATES + (size_t)row * 2048 + 1024 + c0)), rr);
; #pragma unroll
;                         for (int i = 0; i < 8; ++i) acc[ai][bj][m][i >> 2][i & 3] *= rr[i];
;                     } else { float ga[8], o[8]; unpack8(__builtin_nontemporal_load((const u32x4*)(GATES + (size_t)row * 2048 + c0)), ga);
; #pragma unroll
;                         for (int i = 0; i < 8; ++i) o[i] = ga[i] * acc[ai][bj][m][i >> 2][i & 3];
;                         *(u32x4*)(U + (size_t)row * DM + c0) = pack8(o); }
	v_lshlrev_b32_e32 v148, 16, v182
	v_and_b32_e32 v149, 0xffff0000, v182
	v_lshlrev_b32_e32 v238, 16, v183
	v_and_b32_e32 v239, 0xffff0000, v183
	v_lshlrev_b32_e32 v182, 16, v184
	v_and_b32_e32 v183, 0xffff0000, v184
	v_lshlrev_b32_e32 v184, 16, v185
	v_and_b32_e32 v185, 0xffff0000, v185
	v_pk_mul_f32 v[148:149], v[76:77], v[148:149]
	v_pk_mul_f32 v[238:239], v[78:79], v[238:239]
	v_pk_mul_f32 v[182:183], v[72:73], v[182:183]
	v_pk_mul_f32 v[184:185], v[74:75], v[184:185]
	v_cvt_pk_bf16_f32 v185, v184, v185
	v_cvt_pk_bf16_f32 v184, v182, v183
	v_cvt_pk_bf16_f32 v182, v148, v149
	v_cvt_pk_bf16_f32 v183, v238, v239
	global_store_dwordx4 v241, v[182:185], s[12:13] offset:256 sc1
	s_waitcnt vmcnt(15)
	v_lshlrev_b32_e32 v148, 16, v186
	v_and_b32_e32 v149, 0xffff0000, v186
	v_lshlrev_b32_e32 v238, 16, v187
	v_and_b32_e32 v239, 0xffff0000, v187
	v_lshlrev_b32_e32 v186, 16, v188
	v_and_b32_e32 v187, 0xffff0000, v188
	v_lshlrev_b32_e32 v188, 16, v189
	v_and_b32_e32 v189, 0xffff0000, v189
	v_pk_mul_f32 v[148:149], v[100:101], v[148:149]
	v_pk_mul_f32 v[238:239], v[102:103], v[238:239]
	v_pk_mul_f32 v[186:187], v[96:97], v[186:187]
	v_pk_mul_f32 v[188:189], v[98:99], v[188:189]
	v_add_u32_e32 v241, s19, v154
	v_lshl_add_u32 v241, v241, 11, v240
	v_cvt_pk_bf16_f32 v189, v188, v189
	v_cvt_pk_bf16_f32 v188, v186, v187
	v_cvt_pk_bf16_f32 v186, v148, v149
	v_cvt_pk_bf16_f32 v187, v238, v239
	global_store_dwordx4 v241, v[186:189], s[12:13] offset:0 sc1
	s_waitcnt vmcnt(15)
	v_lshlrev_b32_e32 v148, 16, v190
	v_and_b32_e32 v149, 0xffff0000, v190
	v_lshlrev_b32_e32 v238, 16, v191
	v_and_b32_e32 v239, 0xffff0000, v191
	v_lshlrev_b32_e32 v190, 16, v192
	v_and_b32_e32 v191, 0xffff0000, v192
	v_lshlrev_b32_e32 v192, 16, v193
	v_and_b32_e32 v193, 0xffff0000, v193
	v_pk_mul_f32 v[148:149], v[68:69], v[148:149]
	v_pk_mul_f32 v[238:239], v[70:71], v[238:239]
	v_pk_mul_f32 v[190:191], v[64:65], v[190:191]
	v_pk_mul_f32 v[192:193], v[66:67], v[192:193]
	v_cvt_pk_bf16_f32 v193, v192, v193
	v_cvt_pk_bf16_f32 v192, v190, v191
	v_cvt_pk_bf16_f32 v190, v148, v149
	v_cvt_pk_bf16_f32 v191, v238, v239
	global_store_dwordx4 v241, v[190:193], s[12:13] offset:256 sc1
	s_waitcnt vmcnt(15)
	v_lshlrev_b32_e32 v148, 16, v194
	v_and_b32_e32 v149, 0xffff0000, v194
	v_lshlrev_b32_e32 v238, 16, v195
	v_and_b32_e32 v239, 0xffff0000, v195
	v_lshlrev_b32_e32 v194, 16, v196
	v_and_b32_e32 v195, 0xffff0000, v196
	v_lshlrev_b32_e32 v196, 16, v197
	v_and_b32_e32 v197, 0xffff0000, v197
	v_pk_mul_f32 v[148:149], v[60:61], v[148:149]
	v_pk_mul_f32 v[238:239], v[62:63], v[238:239]
	v_pk_mul_f32 v[194:195], v[56:57], v[194:195]
	v_pk_mul_f32 v[196:197], v[58:59], v[196:197]
	v_add_u32_e32 v241, s19, v155
	v_lshl_add_u32 v241, v241, 11, v240
	v_cvt_pk_bf16_f32 v197, v196, v197
	v_cvt_pk_bf16_f32 v196, v194, v195
	v_cvt_pk_bf16_f32 v194, v148, v149
	v_cvt_pk_bf16_f32 v195, v238, v239
	global_store_dwordx4 v241, v[194:197], s[12:13] offset:0 sc1
	s_waitcnt vmcnt(15)
	v_lshlrev_b32_e32 v148, 16, v198
	v_and_b32_e32 v149, 0xffff0000, v198
	v_lshlrev_b32_e32 v238, 16, v199
	v_and_b32_e32 v239, 0xffff0000, v199
	v_lshlrev_b32_e32 v198, 16, v200
	v_and_b32_e32 v199, 0xffff0000, v200
	v_lshlrev_b32_e32 v200, 16, v201
	v_and_b32_e32 v201, 0xffff0000, v201
	v_pk_mul_f32 v[148:149], v[28:29], v[148:149]
	v_pk_mul_f32 v[238:239], v[30:31], v[238:239]
	v_pk_mul_f32 v[198:199], v[24:25], v[198:199]
	v_pk_mul_f32 v[200:201], v[26:27], v[200:201]
	v_cvt_pk_bf16_f32 v201, v200, v201
	v_cvt_pk_bf16_f32 v200, v198, v199
	v_cvt_pk_bf16_f32 v198, v148, v149
	v_cvt_pk_bf16_f32 v199, v238, v239
	global_store_dwordx4 v241, v[198:201], s[12:13] offset:256 sc1
	s_waitcnt vmcnt(15)
; __device__ __forceinline__ u32x4 pack8(const float (&v)[8]) { u32x4 w; w.x = cvtpk(v[0], v[1]); w.y = cvtpk(v[2], v[3]); w.z = cvtpk(v[4], v[5]); w.w = cvtpk(v[6], v[7]); return w; }
;     __device__ __forceinline__ void operator()(pg8::f32x4 (&acc)[2][2][4][2], const pg8::Unit& u, int wr, int wc, int fr, int fq) const {
;     ...
;                     const int row = u.pm * 256 + ai * 128 + wr * 64 + m * 16 + fr, c0 = u.pn * 256 + bj * 128 + wc * 32 + 8 * fq;
;                     if (u.seg == 0) { float rr[8]; unpack8(__builtin_nontemporal_load((const u32x4*)(GATES + (size_t)row * 2048 + 1024 + c0)), rr);
; #pragma unroll
;                         for (int i = 0; i < 8; ++i) acc[ai][bj][m][i >> 2][i & 3] *= rr[i];
;                     } else { float ga[8], o[8]; unpack8(__builtin_nontemporal_load((const u32x4*)(GATES + (size_t)row * 2048 + c0)), ga);
; #pragma unroll
;                         for (int i = 0; i < 8; ++i) o[i] = ga[i] * acc[ai][bj][m][i >> 2][i & 3];
;                         *(u32x4*)(U + (size_t)row * DM + c0) = pack8(o); }
	v_lshlrev_b32_e32 v148, 16, v202
	v_and_b32_e32 v149, 0xffff0000, v202
	v_lshlrev_b32_e32 v238, 16, v203
	v_and_b32_e32 v239, 0xffff0000, v203
	v_lshlrev_b32_e32 v202, 16, v204
	v_and_b32_e32 v203, 0xffff0000, v204
	v_lshlrev_b32_e32 v204, 16, v205
	v_and_b32_e32 v205, 0xffff0000, v205
	v_pk_mul_f32 v[148:149], v[52:53], v[148:149]
	v_pk_mul_f32 v[238:239], v[54:55], v[238:239]
	v_pk_mul_f32 v[202:203], v[48:49], v[202:203]
	v_pk_mul_f32 v[204:205], v[50:51], v[204:205]
	v_add_u32_e32 v241, s19, v156
	v_lshl_add_u32 v241, v241, 11, v240
	v_cvt_pk_bf16_f32 v205, v204, v205
	v_cvt_pk_bf16_f32 v204, v202, v203
	v_cvt_pk_bf16_f32 v202, v148, v149
	v_cvt_pk_bf16_f32 v203, v238, v239
	global_store_dwordx4 v241, v[202:205], s[12:13] offset:0 sc1
	s_waitcnt vmcnt(15)
	v_lshlrev_b32_e32 v148, 16, v210
	v_and_b32_e32 v149, 0xffff0000, v210
	v_lshlrev_b32_e32 v238, 16, v211
	v_and_b32_e32 v239, 0xffff0000, v211
	v_lshlrev_b32_e32 v210, 16, v212
	v_and_b32_e32 v211, 0xffff0000, v212
	v_lshlrev_b32_e32 v212, 16, v213
	v_and_b32_e32 v213, 0xffff0000, v213
	v_pk_mul_f32 v[148:149], v[20:21], v[148:149]
	v_pk_mul_f32 v[238:239], v[22:23], v[238:239]
	v_pk_mul_f32 v[210:211], v[16:17], v[210:211]
	v_pk_mul_f32 v[212:213], v[18:19], v[212:213]
	v_cvt_pk_bf16_f32 v213, v212, v213
	v_cvt_pk_bf16_f32 v212, v210, v211
	v_cvt_pk_bf16_f32 v210, v148, v149
	v_cvt_pk_bf16_f32 v211, v238, v239
	global_store_dwordx4 v241, v[210:213], s[12:13] offset:256 sc1
	s_waitcnt vmcnt(15)
	v_lshlrev_b32_e32 v148, 16, v214
	v_and_b32_e32 v149, 0xffff0000, v214
	v_lshlrev_b32_e32 v238, 16, v215
	v_and_b32_e32 v239, 0xffff0000, v215
	v_lshlrev_b32_e32 v214, 16, v216
	v_and_b32_e32 v215, 0xffff0000, v216
	v_lshlrev_b32_e32 v216, 16, v217
	v_and_b32_e32 v217, 0xffff0000, v217
	v_pk_mul_f32 v[148:149], v[44:45], v[148:149]
	v_pk_mul_f32 v[238:239], v[46:47], v[238:239]
	v_pk_mul_f32 v[214:215], v[40:41], v[214:215]
	v_pk_mul_f32 v[216:217], v[42:43], v[216:217]
	v_add_u32_e32 v241, s19, v157
	v_lshl_add_u32 v241, v241, 11, v240
	v_cvt_pk_bf16_f32 v217, v216, v217
	v_cvt_pk_bf16_f32 v216, v214, v215
	v_cvt_pk_bf16_f32 v214, v148, v149
	v_cvt_pk_bf16_f32 v215, v238, v239
	global_store_dwordx4 v241, v[214:217], s[12:13] offset:0 sc1
	s_waitcnt vmcnt(15)
	v_lshlrev_b32_e32 v148, 16, v218
	v_and_b32_e32 v149, 0xffff0000, v218
	v_lshlrev_b32_e32 v238, 16, v219
	v_and_b32_e32 v239, 0xffff0000, v219
	v_lshlrev_b32_e32 v218, 16, v220
	v_and_b32_e32 v219, 0xffff0000, v220
	v_lshlrev_b32_e32 v220, 16, v221
	v_and_b32_e32 v221, 0xffff0000, v221
	v_pk_mul_f32 v[148:149], v[12:13], v[148:149]
	v_pk_mul_f32 v[238:239], v[14:15], v[238:239]
	v_pk_mul_f32 v[218:219], v[8:9], v[218:219]
	v_pk_mul_f32 v[220:221], v[10:11], v[220:221]
	v_cvt_pk_bf16_f32 v221, v220, v221
	v_cvt_pk_bf16_f32 v220, v218, v219
	v_cvt_pk_bf16_f32 v218, v148, v149
	v_cvt_pk_bf16_f32 v219, v238, v239
	global_store_dwordx4 v241, v[218:221], s[12:13] offset:256 sc1
	s_waitcnt vmcnt(15)
	v_lshlrev_b32_e32 v148, 16, v222
	v_and_b32_e32 v149, 0xffff0000, v222
	v_lshlrev_b32_e32 v238, 16, v223
	v_and_b32_e32 v239, 0xffff0000, v223
	v_lshlrev_b32_e32 v222, 16, v224
	v_and_b32_e32 v223, 0xffff0000, v224
	v_lshlrev_b32_e32 v224, 16, v225
	v_and_b32_e32 v225, 0xffff0000, v225
	v_pk_mul_f32 v[148:149], v[36:37], v[148:149]
	v_pk_mul_f32 v[238:239], v[38:39], v[238:239]
	v_pk_mul_f32 v[222:223], v[32:33], v[222:223]
	v_pk_mul_f32 v[224:225], v[34:35], v[224:225]
	v_add_u32_e32 v241, s19, v158
	v_lshl_add_u32 v241, v241, 11, v240
	v_cvt_pk_bf16_f32 v225, v224, v225
	v_cvt_pk_bf16_f32 v224, v222, v223
	v_cvt_pk_bf16_f32 v222, v148, v149
	v_cvt_pk_bf16_f32 v223, v238, v239
	global_store_dwordx4 v241, v[222:225], s[12:13] offset:0 sc1
	s_waitcnt vmcnt(15)
	v_lshlrev_b32_e32 v148, 16, v144
	v_and_b32_e32 v149, 0xffff0000, v144
	v_lshlrev_b32_e32 v238, 16, v145
	v_and_b32_e32 v239, 0xffff0000, v145
	v_lshlrev_b32_e32 v144, 16, v146
	v_and_b32_e32 v145, 0xffff0000, v146
	v_lshlrev_b32_e32 v146, 16, v147
	v_and_b32_e32 v147, 0xffff0000, v147
	v_pk_mul_f32 v[148:149], v[4:5], v[148:149]
	v_pk_mul_f32 v[238:239], v[6:7], v[238:239]
	v_pk_mul_f32 v[144:145], v[0:1], v[144:145]
	v_pk_mul_f32 v[146:147], v[2:3], v[146:147]
	v_cvt_pk_bf16_f32 v147, v146, v147
	v_cvt_pk_bf16_f32 v146, v144, v145
	v_cvt_pk_bf16_f32 v144, v148, v149
	v_cvt_pk_bf16_f32 v145, v238, v239
	global_store_dwordx4 v241, v[144:147], s[12:13] offset:256 sc1

; __device__ __forceinline__ u32x4 pack8(const float (&v)[8]) { u32x4 w; w.x = cvtpk(v[0], v[1]); w.y = cvtpk(v[2], v[3]); w.z = cvtpk(v[4], v[5]); w.w = cvtpk(v[6], v[7]); return w; }
; #define LAS __attribute__((address_space(3)))
;     __device__ __forceinline__ void operator()(const pg8::f32x4 (&acc)[2][2][4][2], const pg8::Unit& u, int wr, int wc, int fr, int fq) const {
;         LAS char* xl = (LAS char*)xb + ((wr * 64 + fr) * 8 + wc) * 4; asm volatile("" : "+v"(xl));
;         const int b = u.pm >> 4; const float* mb = e.mod + (size_t)b * NMOD;
; #pragma unroll
;         for (int bj = 0; bj < 2; ++bj) {
;             const int c0 = u.pn * 256 + bj * 128 + wc * 32 + 8 * fq; float g1[8], gm[8];
; #pragma unroll
;             for (int h = 0; h < 2; ++h) { const f32x4 a = *(const f32x4*)(mb + 2 * DM + c0 + 4 * h), sc = *(const f32x4*)(mb + 4 * DM + c0 + 4 * h), ng = *(const f32x4*)(e.n2g + c0 + 4 * h);
; #pragma unroll
;                 for (int i = 0; i < 4; ++i) { g1[4 * h + i] = a[i]; gm[4 * h + i] = ng[i] * (1.0f + sc[i]); } }
; #pragma unroll
;             for (int ai = 0; ai < 2; ++ai) {
;                 f32x4 xa[4], xc[4];
; #pragma unroll
;                 for (int m = 0; m < 4; ++m) { const size_t off = (size_t)(u.pm * 256 + ai * 128 + wr * 64 + m * 16 + fr) * DM + c0; xa[m] = __builtin_nontemporal_load((const f32x4*)(e.x + off)); xc[m] = __builtin_nontemporal_load((const f32x4*)(e.x + off + 4)); }
; #pragma unroll
;                 for (int m = 0; m < 4; ++m) { ACC8(v, ai, bj, m); const size_t off = (size_t)(u.pm * 256 + ai * 128 + wr * 64 + m * 16 + fr) * DM + c0;
;                     float o[8], y[8], s = 0.f;
; #pragma unroll
;                     for (int i = 0; i < 8; ++i) { o[i] = (i < 4 ? xa[m][i & 3] : xc[m][i & 3]) + g1[i] * v[i]; s += o[i] * o[i]; y[i] = o[i] * gm[i]; }
;                     *(f32x4*)(e.out + off) = (f32x4){o[0], o[1], o[2], o[3]}; *(f32x4*)(e.out + off + 4) = (f32x4){o[4], o[5], o[6], o[7]};
;                     *(u32x4*)(e.Y2 + off) = pack8(y);
;                     s += __shfl_xor(s, 16); s += __shfl_xor(s, 32);
;                     if (fq == 0) *(LAS float*)(xl + ((ai * 128 + m * 16) * 8 + bj * 4) * 4) = s; }
.LBB9_668:
	s_and_saveexec_b64 s[98:99], s[80:81]
	v_mov_b32_e32 v240, 0x3c40
	v_mov_b32_e32 v241, 1
	global_atomic_add v240, v241, s[90:91]
	s_or_b64 exec, exec, s[98:99]
	s_ashr_i32 s2, s30, 4
	s_mul_hi_i32 s3, s2, 0x6000
	s_mulk_i32 s2, 0x6000
	s_add_u32 s2, s48, s2
	s_addc_u32 s3, s49, s3
	s_add_u32 s34, s2, 0x2000
	s_addc_u32 s35, s3, 0
	s_add_u32 s36, s2, 0x4000
	v_lshl_or_b32 v176, s10, 8, v211
	s_addc_u32 s37, s3, 0
	s_lshl_b32 s11, s30, 8
	v_add_u32_e32 v198, s11, v209
	v_ashrrev_i32_e32 v177, 31, v176
	v_readlane_b32 s60, v251, 0
	v_lshlrev_b64 v[128:129], 2, v[176:177]
	v_readlane_b32 s61, v251, 1
	v_readlane_b32 s74, v251, 14
	v_readlane_b32 s75, v251, 15
	v_ashrrev_i32_e32 v199, 31, v198
	v_mov_b32_e32 v218, v212
	v_lshl_add_u64 v[130:131], s[34:35], 0, v[128:129]
	v_lshl_add_u64 v[132:133], s[36:37], 0, v[128:129]
	v_lshl_add_u64 v[178:179], s[74:75], 0, v[128:129]
	v_lshl_add_u64 v[200:201], s[60:61], 0, v[128:129]
	v_lshlrev_b64 v[128:129], 12, v[198:199]
	global_load_dwordx4 v[190:193], v[132:133], off offset:16
	global_load_dwordx4 v[194:197], v[132:133], off
	global_load_dwordx4 v[222:225], v[178:179], off offset:16
	global_load_dwordx4 v[226:229], v[178:179], off
	v_lshl_add_u64 v[182:183], v[200:201], 0, v[128:129]
	global_load_dwordx4 v[230:233], v[182:183], off nt
	global_load_dwordx4 v[132:135], v[130:131], off
	s_nop 0
	global_load_dwordx4 v[128:131], v[130:131], off offset:16
	s_nop 0
	global_load_dwordx4 v[234:237], v[182:183], off offset:16 nt
	v_or_b32_e32 v206, 16, v198
	v_or_b32_e32 v204, 32, v198
	v_or_b32_e32 v202, 48, v198
	v_ashrrev_i32_e32 v207, 31, v206
	v_ashrrev_i32_e32 v205, 31, v204
	v_ashrrev_i32_e32 v203, 31, v202
	v_lshlrev_b64 v[136:137], 12, v[206:207]
	v_lshlrev_b64 v[138:139], 12, v[204:205]
	v_lshlrev_b64 v[140:141], 12, v[202:203]
	v_lshl_add_u64 v[188:189], v[200:201], 0, v[136:137]
	v_lshl_add_u64 v[186:187], v[200:201], 0, v[138:139]
	v_lshl_add_u64 v[184:185], v[200:201], 0, v[140:141]
	global_load_dwordx4 v[152:155], v[188:189], off offset:16 nt
	global_load_dwordx4 v[156:159], v[188:189], off nt
	global_load_dwordx4 v[144:147], v[186:187], off offset:16 nt
	global_load_dwordx4 v[148:151], v[186:187], off nt
	global_load_dwordx4 v[136:139], v[184:185], off offset:16 nt
	global_load_dwordx4 v[140:143], v[184:185], off nt
	v_and_b32_e32 v181, 64, v217
	v_xor_b32_e32 v180, 16, v217
	v_add_u32_e32 v181, 64, v181
	v_cmp_lt_i32_e32 vcc, v180, v181
	v_xor_b32_e32 v219, 32, v217
	v_readlane_b32 s62, v251, 2
	v_cndmask_b32_e32 v180, v217, v180, vcc
	v_lshlrev_b32_e32 v220, 2, v180
	v_cmp_lt_i32_e32 vcc, v219, v181
	v_readlane_b32 s63, v251, 3
	v_readlane_b32 s64, v251, 4
	v_cndmask_b32_e32 v181, v217, v219, vcc
	v_lshlrev_b32_e32 v219, 2, v181
	v_lshlrev_b64 v[180:181], 10, v[198:199]
	v_lshl_add_u64 v[238:239], v[180:181], 0, v[176:177]
	v_readlane_b32 s65, v251, 5
	v_readlane_b32 s66, v251, 6
	v_readlane_b32 s67, v251, 7
	v_readlane_b32 s68, v251, 8
	v_readlane_b32 s69, v251, 9
	v_readlane_b32 s70, v251, 10
	v_readlane_b32 s71, v251, 11
	v_readlane_b32 s72, v251, 12
	v_readlane_b32 s73, v251, 13
	s_waitcnt vmcnt(0)
	v_pk_add_f32 v[190:191], v[190:191], 1.0 op_sel_hi:[1,0]
	v_pk_add_f32 v[192:193], v[192:193], 1.0 op_sel_hi:[1,0]
	v_pk_mul_f32 v[190:191], v[222:223], v[190:191]
	v_pk_fma_f32 v[222:223], v[124:125], v[132:133], v[230:231]
	v_pk_mul_f32 v[192:193], v[224:225], v[192:193]
	v_pk_fma_f32 v[224:225], v[126:127], v[134:135], v[232:233]
	v_pk_mul_f32 v[126:127], v[222:223], v[222:223]
	v_pk_mul_f32 v[124:125], v[224:225], v[224:225]
	v_add_f32_e32 v126, v126, v127
	v_pk_fma_f32 v[120:121], v[120:121], v[128:129], v[234:235]
	v_add_f32_e32 v124, v124, v126
	v_pk_mul_f32 v[232:233], v[120:121], v[120:121]
	v_add_f32_e32 v124, v125, v124
	v_pk_fma_f32 v[122:123], v[122:123], v[130:131], v[236:237]
	v_add_f32_e32 v124, v232, v124
	v_pk_mul_f32 v[230:231], v[122:123], v[122:123]
	v_add_f32_e32 v124, v233, v124
	v_add_f32_e32 v124, v230, v124
	v_add_f32_e32 v124, v231, v124
	ds_bpermute_b32 v125, v220, v124
	v_lshl_add_u64 v[126:127], v[238:239], 2, s[88:89]
	v_pk_mul_f32 v[234:235], v[190:191], v[120:121]
	global_store_dwordx4 v[126:127], v[222:225], off
	global_store_dwordx4 v[126:127], v[120:123], off offset:16
	v_pk_add_f32 v[194:195], v[194:195], 1.0 op_sel_hi:[1,0]
	v_pk_add_f32 v[196:197], v[196:197], 1.0 op_sel_hi:[1,0]
	s_waitcnt lgkmcnt(0)
	v_add_f32_e32 v120, v124, v125
	ds_bpermute_b32 v121, v219, v120
	v_pk_mul_f32 v[194:195], v[226:227], v[194:195]
	v_pk_mul_f32 v[196:197], v[228:229], v[196:197]
	v_pk_mul_f32 v[226:227], v[194:195], v[222:223]
	v_pk_mul_f32 v[228:229], v[196:197], v[224:225]
	v_pk_mul_f32 v[236:237], v[192:193], v[122:123]
	v_cvt_pk_bf16_f32 v122, v226, v227
	v_cvt_pk_bf16_f32 v123, v228, v229
	v_cvt_pk_bf16_f32 v124, v234, v235
	v_cvt_pk_bf16_f32 v125, v236, v237
	v_lshl_add_u64 v[222:223], v[238:239], 1, s[16:17]
	global_store_dwordx4 v[222:223], v[122:125], off
	s_and_saveexec_b64 s[2:3], s[0:1]
	s_cbranch_execz .LBB9_670
	s_waitcnt lgkmcnt(0)
	v_add_f32_e32 v120, v120, v121
	ds_write_b32 v218, v120

; __device__ __forceinline__ unsigned xb_ld(unsigned* p)              { return __hip_atomic_load(p, __ATOMIC_RELAXED, __HIP_MEMORY_SCOPE_AGENT); }
; __device__ __forceinline__ unsigned xb_add(unsigned* p, unsigned v) { return __hip_atomic_fetch_add(p, v, __ATOMIC_RELAXED, __HIP_MEMORY_SCOPE_AGENT); }
; #define XB_SPIN(cond, bar) do { unsigned _sp = 0; while (cond) { __builtin_amdgcn_s_sleep(1); \
;     if ((++_sp & 255u) == 0u) { if (xb_ld(&(bar)[XB_TMO])) break; if (_sp > XB_SPIN_CAP) { atomicAdd(&(bar)[XB_TMO], 1u); break; } } } } while (0)
; #define SEAM(k) do { if (IN(k) && IN((k) + 1)) GRID_SYNC(); } while (0)
; __device__ __forceinline__ void xcd_barrier(const XcdBarrier& b) {
;     asm volatile("s_waitcnt vmcnt(0)" ::: "memory");
;     __syncthreads();
;     if (threadIdx.x == 0) {
;         unsigned* bar = b.bar;
;         __builtin_amdgcn_s_waitcnt(0);
;         unsigned nloc = b.st[0], nx = b.st[1];
;         if (nloc == 0u) { xcd_barrier_complete(bar, b.x, nloc, nx); b.st[0] = nloc; b.st[1] = nx; }
;         const unsigned old = xb_add(&bar[XB_XSUB(b.x)], 1u);
;         const unsigned gen = old / nloc;
;         if (old + 1u == (gen + 1u) * nloc) {
;             __builtin_amdgcn_fence(__ATOMIC_RELEASE, "agent");
;             asm volatile("s_waitcnt vmcnt(0)" ::: "memory");
;             const unsigned og = xb_add(&bar[XB_TOP], 1u);
;             const unsigned tg = og / nx;
;             if (og + 1u == (tg + 1u) * nx) xb_add(&bar[XB_TOPGEN], 1u);
;             else XB_SPIN(xb_ld(&bar[XB_TOPGEN]) == tg, bar);
;             __builtin_amdgcn_fence(__ATOMIC_ACQUIRE, "agent");
;             xb_add(&bar[XB_XGEN(b.x)], 1u);
;             asm volatile("s_waitcnt vmcnt(0)" ::: "memory");
;         } else {
;             XB_SPIN(xb_ld(&bar[XB_XGEN(b.x)]) == gen, bar);
;             __builtin_amdgcn_fence(__ATOMIC_ACQUIRE, "agent");
;             asm volatile("s_waitcnt vmcnt(0)" ::: "memory");
;         }
;     }
;     __syncthreads();
; }
; __global__ void __launch_bounds__(NTHR, 2) mk_fwd(MkArgs a) {
;     ...
;     SEAM(5);
.LBB9_706:
	s_cmp_gt_i32 s93, 6
	s_cselect_b64 s[0:1], -1, 0
	s_and_b64 s[2:3], s[8:9], s[0:1]
	s_andn2_b64 vcc, exec, s[2:3]
	s_cbranch_vccnz .LBB9_760
	s_waitcnt vmcnt(0)
	s_waitcnt vmcnt(0) lgkmcnt(0)
	s_barrier
	s_and_saveexec_b64 s[4:5], s[80:81]
	s_cbranch_execz .LBB9_759
	v_mov_b32_e32 v0, 0x24008
	ds_read_b32 v0, v0
	s_waitcnt lgkmcnt(0)
	v_readfirstlane_b32 s98, v0
	s_nop 3
	s_cmp_eq_u32 s98, 1
	s_cbranch_scc0 .Lgb5_orig
	s_cmpk_lg_i32 s94, 0x100
	s_cbranch_scc1 .Lgb5_orig
	s_and_b32 s98, s97, 63
	s_lshl_b32 s98, s98, 2
	s_add_i32 s98, s98, 0x3d00
	v_mov_b32_e32 v0, s98
	v_mov_b32_e32 v1, 0x100
	global_atomic_add v0, v1, s[90:91]
	buffer_inv sc1
	v_mov_b32_e32 v1, 0x3c40
.Lgb5_poll:
	s_sleep 1
	global_load_dword v2, v0, s[90:91] sc1
	global_load_dword v3, v1, s[90:91] sc1
	s_waitcnt vmcnt(0)
	v_cmp_gt_u32_e32 vcc, 0x400, v2
	s_cbranch_vccnz .Lgb5_poll
	v_cmp_gt_u32_e32 vcc, 0x100, v3
	s_cbranch_vccnz .Lgb5_poll
	s_branch .LBB9_759
